# P2 attention epilogue: all 8 silu-gate row loads issued together after the cross-wave barrier into dead registers (were 8 serial load-wait pairs per item)
# speedup vs baseline: 1.0061x; 1.0033x over previous
.LBB0_265:
	v_mov_b32_e32 v64, v202
	s_nop 1
	v_permlane32_swap_b32_e32 v202, v64
	v_add_f32_e32 v64, v202, v64
	v_div_scale_f32 v65, s[8:9], v64, v64, 1.0
	v_rcp_f32_e32 v66, v65
	v_lshlrev_b32_e32 v67, 2, v184
	v_lshlrev_b32_e32 v68, 2, v200
	v_add3_u32 v72, 0, v67, v68
	v_fma_f32 v67, -v65, v66, 1.0
	v_fmac_f32_e32 v66, v67, v66
	v_div_scale_f32 v67, vcc, 1.0, v64, 1.0
	v_mul_f32_e32 v68, v67, v66
	v_fma_f32 v69, -v65, v68, v67
	v_fmac_f32_e32 v68, v69, v66
	v_fma_f32 v65, -v65, v68, v67
	v_div_fmas_f32 v65, v65, v66, v68
	v_div_fixup_f32 v74, v65, v64, 1.0
	v_pk_mul_f32 v[70:71], v[48:49], v[74:75] op_sel_hi:[1,0]
	v_pk_mul_f32 v[68:69], v[50:51], v[74:75] op_sel_hi:[1,0]
	v_mul_f32_e32 v50, v71, v71
	v_fmac_f32_e32 v50, v70, v70
	v_fmac_f32_e32 v50, v68, v68
	v_pk_mul_f32 v[66:67], v[52:53], v[74:75] op_sel_hi:[1,0]
	v_fmac_f32_e32 v50, v69, v69
	v_fmac_f32_e32 v50, v66, v66
	v_pk_mul_f32 v[64:65], v[54:55], v[74:75] op_sel_hi:[1,0]
	v_fmac_f32_e32 v50, v67, v67
	v_fmac_f32_e32 v50, v64, v64
	v_pk_mul_f32 v[56:57], v[56:57], v[74:75] op_sel_hi:[1,0]
	v_fmac_f32_e32 v50, v65, v65
	v_fmac_f32_e32 v50, v56, v56
	v_pk_mul_f32 v[58:59], v[58:59], v[74:75] op_sel_hi:[1,0]
	v_fmac_f32_e32 v50, v57, v57
	v_fmac_f32_e32 v50, v58, v58
	v_pk_mul_f32 v[60:61], v[60:61], v[74:75] op_sel_hi:[1,0]
	v_fmac_f32_e32 v50, v59, v59
	v_fmac_f32_e32 v50, v60, v60
	v_pk_mul_f32 v[62:63], v[62:63], v[74:75] op_sel_hi:[1,0]
	v_fmac_f32_e32 v50, v61, v61
	v_fmac_f32_e32 v50, v62, v62
	v_fmac_f32_e32 v50, v63, v63
	v_pk_mul_f32 v[54:55], v[32:33], v[74:75] op_sel_hi:[1,0]
	v_pk_mul_f32 v[52:53], v[34:35], v[74:75] op_sel_hi:[1,0]
	v_fmac_f32_e32 v50, v54, v54
	v_fmac_f32_e32 v50, v55, v55
	v_fmac_f32_e32 v50, v52, v52
	v_pk_mul_f32 v[48:49], v[36:37], v[74:75] op_sel_hi:[1,0]
	v_fmac_f32_e32 v50, v53, v53
	v_fmac_f32_e32 v50, v48, v48
	v_pk_mul_f32 v[38:39], v[38:39], v[74:75] op_sel_hi:[1,0]
	v_fmac_f32_e32 v50, v49, v49
	v_fmac_f32_e32 v50, v38, v38
	v_pk_mul_f32 v[40:41], v[40:41], v[74:75] op_sel_hi:[1,0]
	v_fmac_f32_e32 v50, v39, v39
	v_fmac_f32_e32 v50, v40, v40
	v_pk_mul_f32 v[42:43], v[42:43], v[74:75] op_sel_hi:[1,0]
	v_fmac_f32_e32 v50, v41, v41
	v_fmac_f32_e32 v50, v42, v42
	v_pk_mul_f32 v[44:45], v[44:45], v[74:75] op_sel_hi:[1,0]
	v_fmac_f32_e32 v50, v43, v43
	v_fmac_f32_e32 v50, v44, v44
	v_pk_mul_f32 v[46:47], v[46:47], v[74:75] op_sel_hi:[1,0]
	v_fmac_f32_e32 v50, v45, v45
	v_fmac_f32_e32 v50, v46, v46
	v_fmac_f32_e32 v50, v47, v47
	v_mov_b32_e32 v32, v50
	s_nop 1
	v_permlane32_swap_b32_e32 v50, v32
	s_and_saveexec_b64 s[42:43], s[0:1]
	v_add_f32_e32 v32, v50, v32
	ds_write_b32 v72, v32
	s_or_b64 exec, exec, s[42:43]
	v_mov_b32_e32 v32, v181
	s_nop 1
	v_permlane32_swap_b32_e32 v181, v32
	v_add_f32_e32 v32, v181, v32
	v_div_scale_f32 v33, s[8:9], v32, v32, 1.0
	v_rcp_f32_e32 v34, v33
	s_nop 0
	v_fma_f32 v35, -v33, v34, 1.0
	v_fmac_f32_e32 v34, v35, v34
	v_div_scale_f32 v35, vcc, 1.0, v32, 1.0
	v_mul_f32_e32 v36, v35, v34
	v_fma_f32 v37, -v33, v36, v35
	v_fmac_f32_e32 v36, v37, v34
	v_fma_f32 v33, -v33, v36, v35
	v_div_fmas_f32 v33, v33, v34, v36
	v_div_fixup_f32 v34, v33, v32, 1.0
	v_pk_mul_f32 v[16:17], v[16:17], v[34:35] op_sel_hi:[1,0]
	v_pk_mul_f32 v[18:19], v[18:19], v[34:35] op_sel_hi:[1,0]
	v_mul_f32_e32 v32, v17, v17
	v_fmac_f32_e32 v32, v16, v16
	v_fmac_f32_e32 v32, v18, v18
	v_pk_mul_f32 v[20:21], v[20:21], v[34:35] op_sel_hi:[1,0]
	v_fmac_f32_e32 v32, v19, v19
	v_fmac_f32_e32 v32, v20, v20
	v_pk_mul_f32 v[22:23], v[22:23], v[34:35] op_sel_hi:[1,0]
	v_fmac_f32_e32 v32, v21, v21
	v_fmac_f32_e32 v32, v22, v22
	v_pk_mul_f32 v[24:25], v[24:25], v[34:35] op_sel_hi:[1,0]
	v_fmac_f32_e32 v32, v23, v23
	v_fmac_f32_e32 v32, v24, v24
	v_pk_mul_f32 v[26:27], v[26:27], v[34:35] op_sel_hi:[1,0]
	v_fmac_f32_e32 v32, v25, v25
	v_fmac_f32_e32 v32, v26, v26
	v_pk_mul_f32 v[28:29], v[28:29], v[34:35] op_sel_hi:[1,0]
	v_fmac_f32_e32 v32, v27, v27
	v_fmac_f32_e32 v32, v28, v28
	v_pk_mul_f32 v[30:31], v[30:31], v[34:35] op_sel_hi:[1,0]
	v_fmac_f32_e32 v32, v29, v29
	v_fmac_f32_e32 v32, v30, v30
	v_fmac_f32_e32 v32, v31, v31
	v_pk_mul_f32 v[0:1], v[0:1], v[34:35] op_sel_hi:[1,0]
	v_pk_mul_f32 v[2:3], v[2:3], v[34:35] op_sel_hi:[1,0]
	v_fmac_f32_e32 v32, v0, v0
	v_fmac_f32_e32 v32, v1, v1
	v_fmac_f32_e32 v32, v2, v2
	v_pk_mul_f32 v[4:5], v[4:5], v[34:35] op_sel_hi:[1,0]
	v_fmac_f32_e32 v32, v3, v3
	v_fmac_f32_e32 v32, v4, v4
	v_pk_mul_f32 v[6:7], v[6:7], v[34:35] op_sel_hi:[1,0]
	v_fmac_f32_e32 v32, v5, v5
	v_fmac_f32_e32 v32, v6, v6
	v_pk_mul_f32 v[8:9], v[8:9], v[34:35] op_sel_hi:[1,0]
	v_fmac_f32_e32 v32, v7, v7
	v_fmac_f32_e32 v32, v8, v8
	v_pk_mul_f32 v[10:11], v[10:11], v[34:35] op_sel_hi:[1,0]
	v_fmac_f32_e32 v32, v9, v9
	v_fmac_f32_e32 v32, v10, v10
	v_pk_mul_f32 v[12:13], v[12:13], v[34:35] op_sel_hi:[1,0]
	v_fmac_f32_e32 v32, v11, v11
	v_fmac_f32_e32 v32, v12, v12
	v_pk_mul_f32 v[14:15], v[14:15], v[34:35] op_sel_hi:[1,0]
	v_fmac_f32_e32 v32, v13, v13
	v_fmac_f32_e32 v32, v14, v14
	v_fmac_f32_e32 v32, v15, v15
	v_mov_b32_e32 v33, v32
	s_nop 1
	v_permlane32_swap_b32_e32 v32, v33
	s_and_saveexec_b64 s[42:43], s[0:1]
	v_add_f32_e32 v32, v32, v33
	ds_write_b32 v72, v32 offset:128
	s_or_b64 exec, exec, s[42:43]
	v_lshlrev_b64 v[36:37], 1, v[184:185]
	v_lshl_add_u64 v[32:33], s[72:73], 0, v[188:189]
	v_lshlrev_b32_e32 v178, 1, v186
	v_lshl_add_u64 v[32:33], v[32:33], 0, v[36:37]
	v_lshl_add_u64 v[32:33], v[32:33], 0, v[178:179]
	v_add_co_u32_e32 v34, vcc, s46, v32
	s_waitcnt lgkmcnt(0)
	s_nop 0
	v_addc_co_u32_e32 v35, vcc, 0, v33, vcc
	s_barrier
	global_load_dwordx4 v[74:77], v[34:35], off offset:512
	global_load_dwordx4 v[128:131], v[34:35], off offset:544
	global_load_dwordx4 v[132:135], v[34:35], off offset:576
	global_load_dwordx4 v[136:139], v[34:35], off offset:608
	v_lshl_add_u64 v[156:157], v[32:33], 0, s[12:13]
	global_load_dwordx4 v[140:143], v[156:157], off
	global_load_dwordx4 v[144:147], v[156:157], off offset:32
	global_load_dwordx4 v[148:151], v[156:157], off offset:64
	global_load_dwordx4 v[152:155], v[156:157], off offset:96
	v_lshl_add_u32 v72, v200, 2, 0
	ds_read2st64_b32 v[34:35], v72 offset1:1
	ds_read2st64_b32 v[50:51], v72 offset0:2 offset1:3
	ds_read2st64_b32 v[78:79], v72 offset0:4 offset1:5
	ds_read2st64_b32 v[80:81], v72 offset0:6 offset1:7
	v_mov_b32_e32 v82, v65
	s_waitcnt lgkmcnt(3)
	v_add_f32_e32 v34, 0, v34
	v_add_f32_e32 v34, v34, v35
	s_waitcnt lgkmcnt(2)
	v_add_f32_e32 v34, v34, v50
	v_add_f32_e32 v34, v34, v51
	s_waitcnt lgkmcnt(1)
	v_add_f32_e32 v34, v34, v78
	v_add_f32_e32 v34, v34, v79
	s_waitcnt lgkmcnt(0)
	v_add_f32_e32 v34, v34, v80
	v_add_f32_e32 v34, v34, v81
	v_fmamk_f32 v34, v34, 0x3b000000, v196
	v_mul_f32_e32 v35, 0x4b800000, v34
	v_cmp_gt_f32_e32 vcc, s35, v34
	v_mov_b32_e32 v78, v67
	v_mov_b32_e32 v80, v64
	v_cndmask_b32_e32 v34, v34, v35, vcc
	v_lshl_add_u64 v[36:37], s[20:21], 0, v[36:37]
	s_waitcnt vmcnt(2)
	v_lshl_add_u32 v164, v180, 3, s66
	s_mov_b32 s8, 0
	s_mov_b64 s[0:1], -1
	s_waitcnt vmcnt(0)
	v_mov_b32_e32 v73, v76
	s_nop 1
	v_permlane32_swap_b32_e32 v74, v73
	v_lshlrev_b32_e32 v51, 16, v74
	v_mul_f32_e32 v50, 0xbfb8aa3b, v51
	v_exp_f32_e32 v50, v50
	v_rsq_f32_e32 v76, v34
	v_mov_b32_e32 v83, v77
	s_nop 1
	v_permlane32_swap_b32_e32 v75, v83
	v_add_f32_e32 v34, 1.0, v50
	v_rcp_f32_e32 v35, v34
	v_mul_f32_e32 v50, 0x45800000, v76
	v_mov_b32_e32 v34, v70
	v_cndmask_b32_e32 v50, v76, v50, vcc
	v_pk_mul_f32 v[34:35], v[34:35], v[50:51]
	v_and_b32_e32 v51, 0xffff0000, v74
	v_mul_f32_e32 v70, 0xbfb8aa3b, v51
	v_exp_f32_e32 v74, v70
	v_mov_b32_e32 v70, v71
	v_mov_b32_e32 v76, v68
	v_mul_f32_e32 v34, v34, v35
	v_add_f32_e32 v71, 1.0, v74
	v_rcp_f32_e32 v71, v71
	s_nop 0
	v_pk_mul_f32 v[70:71], v[70:71], v[50:51]
	v_lshlrev_b32_e32 v51, 16, v75
	v_mul_f32_e32 v74, 0xbfb8aa3b, v51
	v_exp_f32_e32 v74, v74
	s_nop 0
	v_add_f32_e32 v74, 1.0, v74
	v_rcp_f32_e32 v77, v74
	v_mov_b32_e32 v74, v69
	v_pk_mul_f32 v[76:77], v[76:77], v[50:51]
	v_and_b32_e32 v51, 0xffff0000, v75
	v_mul_f32_e32 v68, 0xbfb8aa3b, v51
	v_exp_f32_e32 v68, v68
	v_mul_f32_e32 v67, v76, v77
	v_add_f32_e32 v68, 1.0, v68
	v_rcp_f32_e32 v75, v68
	s_nop 0
	v_pk_mul_f32 v[68:69], v[74:75], v[50:51]
	v_lshlrev_b32_e32 v51, 16, v73
	v_mul_f32_e32 v74, 0xbfb8aa3b, v51
	v_exp_f32_e32 v74, v74
	v_mul_f32_e32 v68, v68, v69
	v_add_f32_e32 v74, 1.0, v74
	v_rcp_f32_e32 v75, v74
	v_mov_b32_e32 v74, v66
	v_pk_mul_f32 v[74:75], v[74:75], v[50:51]
	v_and_b32_e32 v51, 0xffff0000, v73
	v_mul_f32_e32 v66, 0xbfb8aa3b, v51
	v_exp_f32_e32 v66, v66
	s_nop 0
	v_add_f32_e32 v66, 1.0, v66
	v_rcp_f32_e32 v79, v66
	s_nop 0
	v_pk_mul_f32 v[78:79], v[78:79], v[50:51]
	v_lshlrev_b32_e32 v51, 16, v83
	v_mul_f32_e32 v64, 0xbfb8aa3b, v51
	v_exp_f32_e32 v66, v64
	v_lshl_add_u64 v[64:65], v[32:33], 0, s[6:7]
	v_add_f32_e32 v35, 1.0, v66
	v_rcp_f32_e32 v81, v35
	v_mul_f32_e32 v35, v70, v71
	v_cvt_pk_bf16_f32 v66, v34, v35
	v_cvt_pk_bf16_f32 v67, v67, v68
	v_pk_mul_f32 v[34:35], v[80:81], v[50:51]
	v_and_b32_e32 v51, 0xffff0000, v83
	v_mul_f32_e32 v70, 0xbfb8aa3b, v51
	v_exp_f32_e32 v70, v70
	v_mul_f32_e32 v68, v74, v75
	v_mov_b32_e32 v80, v63
	v_add_f32_e32 v69, 1.0, v70
	v_rcp_f32_e32 v83, v69
	v_mul_f32_e32 v69, v78, v79
	v_cvt_pk_bf16_f32 v68, v68, v69
	v_mul_f32_e32 v69, v34, v35
	v_pk_mul_f32 v[34:35], v[82:83], v[50:51]
	v_permlane32_swap_b32_e32 v66, v68
	v_mul_f32_e32 v34, v34, v35
	v_cvt_pk_bf16_f32 v69, v69, v34
	v_mov_b64_e32 v[74:75], v[128:129]
	v_mov_b64_e32 v[76:77], v[130:131]
	v_permlane32_swap_b32_e32 v67, v69
	v_mov_b32_e32 v73, v76
	s_nop 1
	v_permlane32_swap_b32_e32 v74, v73
	v_lshlrev_b32_e32 v51, 16, v74
	v_mul_f32_e32 v34, 0xbfb8aa3b, v51
	v_exp_f32_e32 v34, v34
	v_mov_b32_e32 v81, v77
	s_nop 1
	v_permlane32_swap_b32_e32 v75, v81
	v_add_f32_e32 v34, 1.0, v34
	v_rcp_f32_e32 v35, v34
	v_mov_b32_e32 v34, v56
	v_pk_mul_f32 v[70:71], v[34:35], v[50:51]
	v_and_b32_e32 v51, 0xffff0000, v74
	v_mul_f32_e32 v34, 0xbfb8aa3b, v51
	v_exp_f32_e32 v35, v34
	v_mov_b32_e32 v34, v57
	v_add_f32_e32 v35, 1.0, v35
	v_rcp_f32_e32 v35, v35
	s_nop 0
	v_pk_mul_f32 v[76:77], v[34:35], v[50:51]
	v_lshlrev_b32_e32 v51, 16, v75
	v_mul_f32_e32 v34, 0xbfb8aa3b, v51
	v_exp_f32_e32 v34, v34
	s_nop 0
	v_add_f32_e32 v34, 1.0, v34
	v_rcp_f32_e32 v35, v34
	v_mov_b32_e32 v34, v58
	v_mov_b32_e32 v58, v61
	v_pk_mul_f32 v[78:79], v[34:35], v[50:51]
	v_and_b32_e32 v51, 0xffff0000, v75
	v_mul_f32_e32 v34, 0xbfb8aa3b, v51
	v_exp_f32_e32 v34, v34
	s_nop 0
	v_add_f32_e32 v34, 1.0, v34
	v_rcp_f32_e32 v35, v34
	v_mov_b32_e32 v34, v59
	v_pk_mul_f32 v[74:75], v[34:35], v[50:51]
	v_lshlrev_b32_e32 v51, 16, v73
	v_mul_f32_e32 v34, 0xbfb8aa3b, v51
	v_exp_f32_e32 v56, v34
	v_lshlrev_b64 v[34:35], 11, v[182:183]
	v_add_f32_e32 v56, 1.0, v56
	v_rcp_f32_e32 v57, v56
	v_mov_b32_e32 v56, v60
	v_pk_mul_f32 v[60:61], v[56:57], v[50:51]
	v_and_b32_e32 v51, 0xffff0000, v73
	v_mul_f32_e32 v56, 0xbfb8aa3b, v51
	v_exp_f32_e32 v59, v56
	v_lshl_add_u64 v[56:57], v[36:37], 0, v[34:35]
	v_lshl_add_u64 v[56:57], v[56:57], 0, v[178:179]
	global_store_dwordx4 v[56:57], v[66:69], off
	v_add_f32_e32 v59, 1.0, v59
	v_rcp_f32_e32 v59, v59
	v_mul_f32_e32 v60, v60, v61
	v_mul_f32_e32 v67, v74, v75
	v_mov_b32_e32 v74, v39
	v_pk_mul_f32 v[82:83], v[58:59], v[50:51]
	v_lshlrev_b32_e32 v51, 16, v81
	v_mul_f32_e32 v58, 0xbfb8aa3b, v51
	v_exp_f32_e32 v58, v58
	v_mul_f32_e32 v59, v70, v71
	v_or_b32_e32 v34, 0x10000, v34
	v_add_f32_e32 v58, 1.0, v58
	v_rcp_f32_e32 v63, v58
	v_mul_f32_e32 v58, v76, v77
	v_cvt_pk_bf16_f32 v58, v59, v58
	v_mul_f32_e32 v59, v78, v79
	v_pk_mul_f32 v[62:63], v[62:63], v[50:51]
	v_and_b32_e32 v51, 0xffff0000, v81
	v_mul_f32_e32 v66, 0xbfb8aa3b, v51
	v_exp_f32_e32 v66, v66
	v_cvt_pk_bf16_f32 v59, v59, v67
	s_nop 0
	v_add_f32_e32 v61, 1.0, v66
	v_rcp_f32_e32 v81, v61
	v_mul_f32_e32 v61, v82, v83
	v_cvt_pk_bf16_f32 v60, v60, v61
	v_mul_f32_e32 v61, v62, v63
	v_pk_mul_f32 v[62:63], v[80:81], v[50:51]
	v_permlane32_swap_b32_e32 v58, v60
	v_mul_f32_e32 v51, v62, v63
	v_cvt_pk_bf16_f32 v61, v61, v51
	v_mov_b64_e32 v[66:67], v[132:133]
	v_mov_b64_e32 v[68:69], v[134:135]
	v_permlane32_swap_b32_e32 v59, v61
	global_store_dwordx4 v[56:57], v[58:61], off offset:32
	v_mov_b32_e32 v73, v68
	s_nop 1
	v_permlane32_swap_b32_e32 v66, v73
	v_lshlrev_b32_e32 v51, 16, v66
	v_mul_f32_e32 v62, 0xbfb8aa3b, v51
	v_exp_f32_e32 v62, v62
	v_mov_b32_e32 v75, v69
	s_nop 1
	v_permlane32_swap_b32_e32 v67, v75
	v_add_f32_e32 v62, 1.0, v62
	v_rcp_f32_e32 v63, v62
	v_mov_b32_e32 v62, v54
	v_mov_b32_e32 v68, v52
	v_pk_mul_f32 v[62:63], v[62:63], v[50:51]
	v_and_b32_e32 v51, 0xffff0000, v66
	v_mul_f32_e32 v54, 0xbfb8aa3b, v51
	v_exp_f32_e32 v66, v54
	v_mov_b32_e32 v54, v55
	v_add_f32_e32 v55, 1.0, v66
	v_rcp_f32_e32 v55, v55
	s_nop 0
	v_pk_mul_f32 v[54:55], v[54:55], v[50:51]
	v_lshlrev_b32_e32 v51, 16, v67
	v_mul_f32_e32 v66, 0xbfb8aa3b, v51
	v_exp_f32_e32 v66, v66
	s_nop 0
	v_add_f32_e32 v66, 1.0, v66
	v_rcp_f32_e32 v69, v66
	v_mov_b32_e32 v66, v53
	v_pk_mul_f32 v[68:69], v[68:69], v[50:51]
	v_and_b32_e32 v51, 0xffff0000, v67
	v_mul_f32_e32 v52, 0xbfb8aa3b, v51
	v_exp_f32_e32 v52, v52
	s_nop 0
	v_add_f32_e32 v52, 1.0, v52
	v_rcp_f32_e32 v67, v52
	s_nop 0
	v_pk_mul_f32 v[66:67], v[66:67], v[50:51]
	v_lshlrev_b32_e32 v51, 16, v73
	v_mul_f32_e32 v52, 0xbfb8aa3b, v51
	v_exp_f32_e32 v52, v52
	s_nop 0
	v_add_f32_e32 v52, 1.0, v52
	v_rcp_f32_e32 v53, v52
	v_mov_b32_e32 v52, v48
	v_pk_mul_f32 v[70:71], v[52:53], v[50:51]
	v_and_b32_e32 v51, 0xffff0000, v73
	v_mul_f32_e32 v48, 0xbfb8aa3b, v51
	v_exp_f32_e32 v52, v48
	v_mov_b32_e32 v48, v49
	v_mul_f32_e32 v53, v54, v55
	v_mul_f32_e32 v55, v66, v67
	v_add_f32_e32 v49, 1.0, v52
	v_rcp_f32_e32 v49, v49
	v_mul_f32_e32 v52, v62, v63
	v_cvt_pk_bf16_f32 v52, v52, v53
	v_mul_f32_e32 v53, v68, v69
	v_pk_mul_f32 v[48:49], v[48:49], v[50:51]
	v_lshlrev_b32_e32 v51, 16, v75
	v_mul_f32_e32 v39, 0xbfb8aa3b, v51
	v_exp_f32_e32 v39, v39
	v_mul_f32_e32 v48, v48, v49
	v_cvt_pk_bf16_f32 v53, v53, v55
	v_mul_f32_e32 v55, v70, v71
	v_add_f32_e32 v39, 1.0, v39
	v_rcp_f32_e32 v39, v39
	s_nop 0
	v_pk_mul_f32 v[38:39], v[38:39], v[50:51]
	v_and_b32_e32 v51, 0xffff0000, v75
	v_mul_f32_e32 v54, 0xbfb8aa3b, v51
	v_exp_f32_e32 v54, v54
	s_nop 0
	v_add_f32_e32 v54, 1.0, v54
	v_rcp_f32_e32 v75, v54
	v_cvt_pk_bf16_f32 v54, v55, v48
	v_mul_f32_e32 v48, v38, v39
	v_permlane32_swap_b32_e32 v52, v54
	v_pk_mul_f32 v[38:39], v[74:75], v[50:51]
	s_nop 0
	v_mul_f32_e32 v38, v38, v39
	v_cvt_pk_bf16_f32 v55, v48, v38
	v_mov_b64_e32 v[58:59], v[136:137]
	v_mov_b64_e32 v[60:61], v[138:139]
	v_permlane32_swap_b32_e32 v53, v55
	global_store_dwordx4 v[56:57], v[52:55], off offset:64
	v_permlane32_swap_b32_e32 v58, v60
	v_lshlrev_b32_e32 v51, 16, v58
	v_mul_f32_e32 v38, 0xbfb8aa3b, v51
	v_exp_f32_e32 v38, v38
	v_permlane32_swap_b32_e32 v59, v61
	v_add_u32_e32 v52, 0x80, v72
	v_add_f32_e32 v38, 1.0, v38
	v_rcp_f32_e32 v39, v38
	v_mov_b32_e32 v38, v40
	v_pk_mul_f32 v[38:39], v[38:39], v[50:51]
	v_and_b32_e32 v51, 0xffff0000, v58
	v_mul_f32_e32 v40, 0xbfb8aa3b, v51
	v_exp_f32_e32 v48, v40
	v_mov_b32_e32 v40, v41
	v_mov_b32_e32 v58, v43
	v_mul_f32_e32 v38, v38, v39
	v_add_f32_e32 v41, 1.0, v48
	v_rcp_f32_e32 v41, v41
	s_nop 0
	v_pk_mul_f32 v[40:41], v[40:41], v[50:51]
	v_lshlrev_b32_e32 v51, 16, v59
	v_mul_f32_e32 v48, 0xbfb8aa3b, v51
	v_exp_f32_e32 v48, v48
	s_nop 0
	v_add_f32_e32 v48, 1.0, v48
	v_rcp_f32_e32 v49, v48
	v_mov_b32_e32 v48, v42
	v_pk_mul_f32 v[48:49], v[48:49], v[50:51]
	v_and_b32_e32 v51, 0xffff0000, v59
	v_mul_f32_e32 v42, 0xbfb8aa3b, v51
	v_exp_f32_e32 v42, v42
	s_nop 0
	v_add_f32_e32 v42, 1.0, v42
	v_rcp_f32_e32 v59, v42
	s_nop 0
	v_pk_mul_f32 v[42:43], v[58:59], v[50:51]
	v_lshlrev_b32_e32 v51, 16, v60
	v_mul_f32_e32 v58, 0xbfb8aa3b, v51
	v_exp_f32_e32 v58, v58
	v_mul_f32_e32 v42, v42, v43
	v_add_f32_e32 v58, 1.0, v58
	v_rcp_f32_e32 v59, v58
	v_mov_b32_e32 v58, v44
	v_pk_mul_f32 v[58:59], v[58:59], v[50:51]
	v_and_b32_e32 v51, 0xffff0000, v60
	v_mul_f32_e32 v44, 0xbfb8aa3b, v51
	v_exp_f32_e32 v62, v44
	v_mov_b32_e32 v44, v45
	v_mov_b32_e32 v60, v47
	v_add_f32_e32 v45, 1.0, v62
	v_rcp_f32_e32 v45, v45
	v_add_co_u32_e32 v62, vcc, s47, v32
	v_pk_mul_f32 v[44:45], v[44:45], v[50:51]
	v_lshlrev_b32_e32 v51, 16, v61
	v_mul_f32_e32 v47, 0xbfb8aa3b, v51
	v_exp_f32_e32 v47, v47
	v_addc_co_u32_e32 v63, vcc, 0, v33, vcc
	v_add_f32_e32 v39, 1.0, v47
	v_rcp_f32_e32 v47, v39
	v_mul_f32_e32 v39, v40, v41
	v_cvt_pk_bf16_f32 v40, v38, v39
	v_mul_f32_e32 v41, v48, v49
	v_pk_mul_f32 v[38:39], v[46:47], v[50:51]
	v_and_b32_e32 v51, 0xffff0000, v61
	v_mul_f32_e32 v46, 0xbfb8aa3b, v51
	v_exp_f32_e32 v46, v46
	v_cvt_pk_bf16_f32 v41, v41, v42
	v_mul_f32_e32 v42, v58, v59
	v_add_f32_e32 v43, 1.0, v46
	v_rcp_f32_e32 v61, v43
	v_mul_f32_e32 v43, v44, v45
	v_cvt_pk_bf16_f32 v42, v42, v43
	v_mul_f32_e32 v43, v38, v39
	v_pk_mul_f32 v[38:39], v[60:61], v[50:51]
	v_permlane32_swap_b32_e32 v40, v42
	v_mul_f32_e32 v38, v38, v39
	v_cvt_pk_bf16_f32 v43, v43, v38
	v_mov_b64_e32 v[44:45], v[140:141]
	v_mov_b64_e32 v[46:47], v[142:143]
	ds_read2_b32 v[38:39], v72 offset0:32 offset1:96
	ds_read2_b32 v[48:49], v72 offset0:160 offset1:224
	ds_read2st64_b32 v[50:51], v52 offset0:4 offset1:5
	ds_read2st64_b32 v[52:53], v52 offset0:6 offset1:7
	v_permlane32_swap_b32_e32 v41, v43
	global_store_dwordx4 v[56:57], v[40:43], off offset:96
	s_waitcnt lgkmcnt(3)
	v_add_f32_e32 v38, 0, v38
	v_add_f32_e32 v38, v38, v39
	s_waitcnt lgkmcnt(2)
	v_add_f32_e32 v38, v38, v48
	v_add_f32_e32 v38, v38, v49
	s_waitcnt lgkmcnt(1)
	v_add_f32_e32 v38, v38, v50
	v_add_f32_e32 v38, v38, v51
	s_waitcnt lgkmcnt(0)
	v_add_f32_e32 v38, v38, v52
	v_add_f32_e32 v38, v38, v53
	v_fmamk_f32 v38, v38, 0x3b000000, v196
	v_mul_f32_e32 v48, 0x4b800000, v38
	v_cmp_gt_f32_e32 vcc, s35, v38
	v_mov_b32_e32 v52, v46
	s_nop 1
	v_permlane32_swap_b32_e32 v44, v52
	v_lshlrev_b32_e32 v39, 16, v44
	v_mul_f32_e32 v46, 0xbfb8aa3b, v39
	v_exp_f32_e32 v46, v46
	v_cndmask_b32_e32 v38, v38, v48, vcc
	v_rsq_f32_e32 v38, v38
	v_mov_b32_e32 v48, v16
	v_add_f32_e32 v46, 1.0, v46
	v_rcp_f32_e32 v49, v46
	v_mul_f32_e32 v16, 0x45800000, v38
	v_cndmask_b32_e32 v38, v38, v16, vcc
	v_mov_b32_e32 v53, v47
	v_pk_mul_f32 v[48:49], v[48:49], v[38:39]
	v_and_b32_e32 v39, 0xffff0000, v44
	v_mul_f32_e32 v16, 0xbfb8aa3b, v39
	v_exp_f32_e32 v44, v16
	v_mov_b32_e32 v16, v17
	v_permlane32_swap_b32_e32 v45, v53
	v_add_f32_e32 v17, 1.0, v44
	v_rcp_f32_e32 v17, v17
	v_mov_b32_e32 v46, v18
	v_pk_mul_f32 v[16:17], v[16:17], v[38:39]
	v_lshlrev_b32_e32 v39, 16, v45
	v_mul_f32_e32 v44, 0xbfb8aa3b, v39
	v_exp_f32_e32 v44, v44
	v_mul_f32_e32 v16, v16, v17
	v_add_f32_e32 v44, 1.0, v44
	v_rcp_f32_e32 v47, v44
	v_mov_b32_e32 v44, v19
	v_pk_mul_f32 v[46:47], v[46:47], v[38:39]
	v_and_b32_e32 v39, 0xffff0000, v45
	v_mul_f32_e32 v18, 0xbfb8aa3b, v39
	v_exp_f32_e32 v18, v18
	s_nop 0
	v_add_f32_e32 v18, 1.0, v18
	v_rcp_f32_e32 v45, v18
	s_nop 0
	v_pk_mul_f32 v[44:45], v[44:45], v[38:39]
	v_lshlrev_b32_e32 v39, 16, v52
	v_mul_f32_e32 v18, 0xbfb8aa3b, v39
	v_exp_f32_e32 v18, v18
	s_nop 0
	v_add_f32_e32 v18, 1.0, v18
	v_rcp_f32_e32 v19, v18
	v_mov_b32_e32 v18, v20
	v_mov_b32_e32 v20, v21
	v_pk_mul_f32 v[50:51], v[18:19], v[38:39]
	v_and_b32_e32 v39, 0xffff0000, v52
	v_mul_f32_e32 v18, 0xbfb8aa3b, v39
	v_exp_f32_e32 v18, v18
	v_mov_b32_e32 v52, v23
	v_add_f32_e32 v18, 1.0, v18
	v_rcp_f32_e32 v21, v18
	v_lshl_add_u64 v[18:19], v[32:33], 0, s[12:13]
	v_pk_mul_f32 v[32:33], v[20:21], v[38:39]
	v_lshlrev_b32_e32 v39, 16, v53
	v_mul_f32_e32 v20, 0xbfb8aa3b, v39
	v_exp_f32_e32 v20, v20
	v_mul_f32_e32 v21, v48, v49
	v_add_f32_e32 v20, 1.0, v20
	v_rcp_f32_e32 v23, v20
	v_cvt_pk_bf16_f32 v20, v21, v16
	v_mul_f32_e32 v21, v46, v47
	v_pk_mul_f32 v[16:17], v[22:23], v[38:39]
	v_and_b32_e32 v39, 0xffff0000, v53
	v_mul_f32_e32 v22, 0xbfb8aa3b, v39
	v_exp_f32_e32 v22, v22
	v_mul_f32_e32 v23, v44, v45
	v_cvt_pk_bf16_f32 v21, v21, v23
	v_mul_f32_e32 v23, v50, v51
	v_add_f32_e32 v22, 1.0, v22
	v_rcp_f32_e32 v53, v22
	v_mul_f32_e32 v22, v32, v33
	v_cvt_pk_bf16_f32 v22, v23, v22
	v_mul_f32_e32 v23, v16, v17
	v_pk_mul_f32 v[16:17], v[52:53], v[38:39]
	v_permlane32_swap_b32_e32 v20, v22
	v_mul_f32_e32 v16, v16, v17
	v_cvt_pk_bf16_f32 v23, v23, v16
	v_mov_b64_e32 v[40:41], v[144:145]
	v_mov_b64_e32 v[42:43], v[146:147]
	v_permlane32_swap_b32_e32 v21, v23
	v_mov_b32_e32 v44, v42
	s_nop 1
	v_permlane32_swap_b32_e32 v40, v44
	v_lshlrev_b32_e32 v39, 16, v40
	v_mul_f32_e32 v16, 0xbfb8aa3b, v39
	v_exp_f32_e32 v16, v16
	v_mov_b32_e32 v45, v43
	s_nop 1
	v_permlane32_swap_b32_e32 v41, v45
	v_add_f32_e32 v16, 1.0, v16
	v_rcp_f32_e32 v17, v16
	v_mov_b32_e32 v16, v24
	v_pk_mul_f32 v[32:33], v[16:17], v[38:39]
	v_and_b32_e32 v39, 0xffff0000, v40
	v_mul_f32_e32 v16, 0xbfb8aa3b, v39
	v_exp_f32_e32 v17, v16
	v_mov_b32_e32 v16, v25
	v_add_f32_e32 v17, 1.0, v17
	v_rcp_f32_e32 v17, v17
	s_nop 0
	v_pk_mul_f32 v[24:25], v[16:17], v[38:39]
	v_lshlrev_b32_e32 v39, 16, v41
	v_mul_f32_e32 v16, 0xbfb8aa3b, v39
	v_exp_f32_e32 v16, v16
	s_nop 0
	v_add_f32_e32 v16, 1.0, v16
	v_rcp_f32_e32 v17, v16
	v_mov_b32_e32 v16, v26
	v_pk_mul_f32 v[42:43], v[16:17], v[38:39]
	v_and_b32_e32 v39, 0xffff0000, v41
	v_mul_f32_e32 v16, 0xbfb8aa3b, v39
	v_exp_f32_e32 v16, v16
	s_nop 0
	v_add_f32_e32 v16, 1.0, v16
	v_rcp_f32_e32 v17, v16
	v_mov_b32_e32 v16, v27
	v_pk_mul_f32 v[26:27], v[16:17], v[38:39]
	v_lshlrev_b32_e32 v39, 16, v44
	v_mul_f32_e32 v16, 0xbfb8aa3b, v39
	v_exp_f32_e32 v16, v16
	s_nop 0
	v_add_f32_e32 v16, 1.0, v16
	v_rcp_f32_e32 v17, v16
	v_mov_b32_e32 v16, v28
	v_mov_b32_e32 v28, v29
	v_pk_mul_f32 v[40:41], v[16:17], v[38:39]
	v_and_b32_e32 v39, 0xffff0000, v44
	v_mul_f32_e32 v16, 0xbfb8aa3b, v39
	v_exp_f32_e32 v29, v16
	v_mov_b32_e32 v44, v31
	v_lshl_add_u64 v[16:17], v[36:37], 0, v[34:35]
	v_lshl_add_u64 v[16:17], v[16:17], 0, v[178:179]
	v_add_f32_e32 v29, 1.0, v29
	v_rcp_f32_e32 v29, v29
	global_store_dwordx4 v[16:17], v[20:23], off
	v_lshlrev_b32_e32 v178, 5, v199
	v_pk_mul_f32 v[28:29], v[28:29], v[38:39]
	v_lshlrev_b32_e32 v39, 16, v45
	v_mul_f32_e32 v31, 0xbfb8aa3b, v39
	v_exp_f32_e32 v31, v31
	v_mul_f32_e32 v20, v32, v33
	v_mul_f32_e32 v23, v26, v27
	v_add_f32_e32 v21, 1.0, v31
	v_rcp_f32_e32 v31, v21
	v_mul_f32_e32 v21, v24, v25
	v_cvt_pk_bf16_f32 v20, v20, v21
	v_mul_f32_e32 v21, v42, v43
	v_pk_mul_f32 v[24:25], v[30:31], v[38:39]
	v_and_b32_e32 v39, 0xffff0000, v45
	v_mul_f32_e32 v22, 0xbfb8aa3b, v39
	v_exp_f32_e32 v22, v22
	v_cvt_pk_bf16_f32 v21, v21, v23
	v_mul_f32_e32 v23, v40, v41
	v_add_f32_e32 v22, 1.0, v22
	v_rcp_f32_e32 v45, v22
	v_mul_f32_e32 v22, v28, v29
	v_cvt_pk_bf16_f32 v22, v23, v22
	v_mul_f32_e32 v23, v24, v25
	v_pk_mul_f32 v[24:25], v[44:45], v[38:39]
	v_mov_b32_e32 v28, v0
	v_mul_f32_e32 v24, v24, v25
	v_cvt_pk_bf16_f32 v23, v23, v24
	v_mov_b64_e32 v[24:25], v[148:149]
	v_mov_b64_e32 v[26:27], v[150:151]
	v_permlane32_swap_b32_e32 v20, v22
	v_permlane32_swap_b32_e32 v21, v23
	global_store_dwordx4 v[16:17], v[20:23], off offset:32
	v_mov_b32_e32 v30, v26
	s_nop 1
	v_permlane32_swap_b32_e32 v24, v30
	v_lshlrev_b32_e32 v39, 16, v24
	v_mul_f32_e32 v26, 0xbfb8aa3b, v39
	v_exp_f32_e32 v26, v26
	v_mov_b32_e32 v31, v27
	s_nop 1
	v_permlane32_swap_b32_e32 v25, v31
	v_add_f32_e32 v26, 1.0, v26
	v_rcp_f32_e32 v29, v26
	v_mov_b32_e32 v26, v2
	v_lshl_add_u64 v[22:23], s[60:61], 0, v[178:179]
	v_pk_mul_f32 v[28:29], v[28:29], v[38:39]
	v_and_b32_e32 v39, 0xffff0000, v24
	v_mul_f32_e32 v0, 0xbfb8aa3b, v39
	v_exp_f32_e32 v24, v0
	v_mov_b32_e32 v0, v1
	v_mul_f32_e32 v20, v28, v29
	v_add_f32_e32 v1, 1.0, v24
	v_rcp_f32_e32 v1, v1
	s_nop 0
	v_pk_mul_f32 v[0:1], v[0:1], v[38:39]
	v_lshlrev_b32_e32 v39, 16, v25
	v_mul_f32_e32 v24, 0xbfb8aa3b, v39
	v_exp_f32_e32 v24, v24
	v_mul_f32_e32 v0, v0, v1
	v_cvt_pk_bf16_f32 v0, v20, v0
	v_add_f32_e32 v24, 1.0, v24
	v_rcp_f32_e32 v27, v24
	v_mov_b32_e32 v24, v3
	v_pk_mul_f32 v[26:27], v[26:27], v[38:39]
	v_and_b32_e32 v39, 0xffff0000, v25
	v_mul_f32_e32 v2, 0xbfb8aa3b, v39
	v_exp_f32_e32 v2, v2
	v_mul_f32_e32 v1, v26, v27
	v_add_f32_e32 v2, 1.0, v2
	v_rcp_f32_e32 v25, v2
	s_nop 0
	v_pk_mul_f32 v[2:3], v[24:25], v[38:39]
	v_lshlrev_b32_e32 v39, 16, v30
	v_mul_f32_e32 v24, 0xbfb8aa3b, v39
	v_exp_f32_e32 v24, v24
	v_mul_f32_e32 v2, v2, v3
	v_cvt_pk_bf16_f32 v1, v1, v2
	v_add_f32_e32 v24, 1.0, v24
	v_rcp_f32_e32 v25, v24
	v_mov_b32_e32 v24, v4
	v_pk_mul_f32 v[24:25], v[24:25], v[38:39]
	v_and_b32_e32 v39, 0xffff0000, v30
	v_mul_f32_e32 v4, 0xbfb8aa3b, v39
	v_exp_f32_e32 v30, v4
	v_mov_b32_e32 v4, v5
	v_mul_f32_e32 v2, v24, v25
	v_lshl_add_u64 v[24:25], v[22:23], 0, s[36:37]
	v_add_f32_e32 v5, 1.0, v30
	v_rcp_f32_e32 v5, v5
	v_mov_b32_e32 v30, v7
	v_pk_mul_f32 v[4:5], v[4:5], v[38:39]
	v_lshlrev_b32_e32 v39, 16, v31
	v_mul_f32_e32 v7, 0xbfb8aa3b, v39
	v_exp_f32_e32 v7, v7
	s_nop 0
	v_add_f32_e32 v7, 1.0, v7
	v_rcp_f32_e32 v7, v7
	s_nop 0
	v_pk_mul_f32 v[6:7], v[6:7], v[38:39]
	v_and_b32_e32 v39, 0xffff0000, v31
	v_mul_f32_e32 v20, 0xbfb8aa3b, v39
	v_exp_f32_e32 v20, v20
	s_nop 0
	v_add_f32_e32 v3, 1.0, v20
	v_rcp_f32_e32 v31, v3
	v_mul_f32_e32 v3, v4, v5
	v_cvt_pk_bf16_f32 v2, v2, v3
	v_mul_f32_e32 v3, v6, v7
	v_pk_mul_f32 v[4:5], v[30:31], v[38:39]
	v_permlane32_swap_b32_e32 v0, v2
	v_mul_f32_e32 v4, v4, v5
	v_cvt_pk_bf16_f32 v3, v3, v4
	v_mov_b64_e32 v[4:5], v[152:153]
	v_mov_b64_e32 v[6:7], v[154:155]
	v_mov_b32_e32 v18, v8
	v_mov_b32_e32 v8, v9
	v_permlane32_swap_b32_e32 v1, v3
	global_store_dwordx4 v[16:17], v[0:3], off offset:64
	v_mov_b32_e32 v20, v15
	v_mov_b32_e32 v21, v6
	s_nop 1
	v_permlane32_swap_b32_e32 v4, v21
	v_lshlrev_b32_e32 v39, 16, v4
	v_mul_f32_e32 v6, 0xbfb8aa3b, v39
	v_exp_f32_e32 v6, v6
	v_mov_b32_e32 v26, v7
	s_nop 1
	v_permlane32_swap_b32_e32 v5, v26
	v_add_f32_e32 v6, 1.0, v6
	v_rcp_f32_e32 v19, v6
	s_nop 0
	v_pk_mul_f32 v[18:19], v[18:19], v[38:39]
	v_and_b32_e32 v39, 0xffff0000, v4
	v_mul_f32_e32 v4, 0xbfb8aa3b, v39
	v_exp_f32_e32 v4, v4
	s_nop 0
	v_add_f32_e32 v4, 1.0, v4
	v_rcp_f32_e32 v9, v4
	s_nop 0
	v_pk_mul_f32 v[6:7], v[8:9], v[38:39]
	v_lshlrev_b32_e32 v39, 16, v5
	v_mul_f32_e32 v4, 0xbfb8aa3b, v39
	v_exp_f32_e32 v4, v4
	v_mov_b32_e32 v8, v10
	v_mul_f32_e32 v6, v6, v7
	v_add_f32_e32 v4, 1.0, v4
	v_rcp_f32_e32 v9, v4
	s_nop 0
	v_pk_mul_f32 v[8:9], v[8:9], v[38:39]
	v_and_b32_e32 v39, 0xffff0000, v5
	v_mul_f32_e32 v4, 0xbfb8aa3b, v39
	v_exp_f32_e32 v4, v4
	s_nop 0
	v_add_f32_e32 v4, 1.0, v4
	v_rcp_f32_e32 v5, v4
	v_mov_b32_e32 v4, v11
	v_pk_mul_f32 v[4:5], v[4:5], v[38:39]
	v_lshlrev_b32_e32 v39, 16, v21
	v_mul_f32_e32 v10, 0xbfb8aa3b, v39
	v_exp_f32_e32 v11, v10
	v_mov_b32_e32 v10, v13
	v_mul_f32_e32 v4, v4, v5
	v_add_f32_e32 v11, 1.0, v11
	v_rcp_f32_e32 v13, v11
	s_nop 0
	v_pk_mul_f32 v[12:13], v[12:13], v[38:39]
	v_and_b32_e32 v39, 0xffff0000, v21
	v_mul_f32_e32 v11, 0xbfb8aa3b, v39
	v_exp_f32_e32 v11, v11
	v_mul_f32_e32 v7, v12, v13
	v_add_co_u32_e32 v12, vcc, s46, v22
	v_add_f32_e32 v11, 1.0, v11
	v_rcp_f32_e32 v11, v11
	v_addc_co_u32_e32 v13, vcc, 0, v23, vcc
	v_cmp_gt_u32_e32 vcc, s46, v164
	v_pk_mul_f32 v[2:3], v[10:11], v[38:39]
	v_lshlrev_b32_e32 v39, 16, v26
	v_mul_f32_e32 v0, 0xbfb8aa3b, v39
	v_exp_f32_e32 v1, v0
	v_mul_f32_e32 v0, v18, v19
	v_cvt_pk_bf16_f32 v0, v0, v6
	v_mul_f32_e32 v2, v2, v3
	v_add_f32_e32 v1, 1.0, v1
	v_rcp_f32_e32 v15, v1
	v_mul_f32_e32 v1, v8, v9
	v_cvt_pk_bf16_f32 v1, v1, v4
	v_cvt_pk_bf16_f32 v2, v7, v2
	v_pk_mul_f32 v[4:5], v[14:15], v[38:39]
	v_and_b32_e32 v39, 0xffff0000, v26
	v_mul_f32_e32 v6, 0xbfb8aa3b, v39
	v_exp_f32_e32 v6, v6
	v_permlane32_swap_b32_e32 v0, v2
	v_cndmask_b32_e64 v65, 0, 1.0, vcc
	v_add_f32_e32 v3, 1.0, v6
	v_rcp_f32_e32 v21, v3
	v_mul_f32_e32 v3, v4, v5
	v_mov_b32_e32 v66, v65
	v_mov_b32_e32 v68, v65
	v_pk_mul_f32 v[4:5], v[20:21], v[38:39]
	v_mov_b32_e32 v69, v65
	v_mul_f32_e32 v4, v4, v5
	v_cvt_pk_bf16_f32 v3, v3, v4
	s_nop 0
	v_permlane32_swap_b32_e32 v1, v3
	global_store_dwordx4 v[16:17], v[0:3], off offset:96
	global_load_dwordx4 v[0:3], v178, s[60:61] offset:16
	s_nop 0
	global_load_dwordx4 v[4:7], v[24:25], off offset:16
	global_load_dwordx4 v[8:11], v178, s[60:61]
	s_nop 0
	global_load_dwordx4 v[12:15], v[12:13], off
	s_nop 0
	global_load_dwordx4 v[16:19], v178, s[60:61] offset:2064
	global_load_dwordx4 v[20:23], v178, s[60:61] offset:2048
	v_lshlrev_b32_e32 v24, 3, v199
	v_lshlrev_b32_e32 v178, 4, v199
	v_lshl_add_u64 v[70:71], s[72:73], 0, v[178:179]
	v_lshl_add_u64 v[72:73], s[20:21], 0, v[178:179]
	v_lshlrev_b32_e32 v178, 1, v24
	s_waitcnt vmcnt(5)
	v_mov_b32_e32 v74, v2
	s_waitcnt vmcnt(4)
	v_mov_b32_e32 v75, v6
	v_mov_b32_e32 v76, v3
	v_mov_b32_e32 v77, v7
	v_mov_b32_e32 v78, v0
	v_mov_b32_e32 v79, v4
	v_mov_b32_e32 v80, v1
	v_mov_b32_e32 v81, v5
	s_waitcnt vmcnt(3)
	v_mov_b32_e32 v82, v10
	s_waitcnt vmcnt(2)
	v_mov_b32_e32 v83, v14
	v_mov_b32_e32 v84, v11
	v_mov_b32_e32 v85, v15
	v_mov_b32_e32 v86, v8
	v_mov_b32_e32 v87, v12
	v_mov_b32_e32 v88, v9
	v_mov_b32_e32 v89, v13
	v_mov_b32_e32 v90, v2
	s_waitcnt vmcnt(1)
	v_mov_b32_e32 v91, v18
	v_mov_b32_e32 v92, v3
	v_mov_b32_e32 v93, v19
	v_mov_b32_e32 v94, v0
	v_mov_b32_e32 v95, v16
	v_mov_b32_e32 v96, v1
	v_mov_b32_e32 v97, v17
	v_mov_b32_e32 v98, v10
	s_waitcnt vmcnt(0)
	v_mov_b32_e32 v99, v22
	v_mov_b32_e32 v100, v11
	v_mov_b32_e32 v101, v23
	v_mov_b32_e32 v102, v8
	v_mov_b32_e32 v103, v20
	v_mov_b32_e32 v104, v9
	v_mov_b32_e32 v105, v21
	v_mov_b32_e32 v106, v18
	v_mov_b32_e32 v107, v6
	v_mov_b32_e32 v108, v19
	v_mov_b32_e32 v109, v7
	v_mov_b32_e32 v110, v16
	v_mov_b32_e32 v111, v4
	v_mov_b32_e32 v112, v17
	v_mov_b32_e32 v113, v5
	v_mov_b32_e32 v114, v22
	v_mov_b32_e32 v115, v14
	v_mov_b32_e32 v116, v23
	v_mov_b32_e32 v117, v15
	v_mov_b32_e32 v118, v20
	v_mov_b32_e32 v119, v12
	v_mov_b32_e32 v120, v21
	v_mov_b32_e32 v121, v13
